# S2 (QK^T, QS) stage of all three scan cores software-pipelined with counted lgkmcnt; masked products unconditional
# speedup vs baseline: 1.0284x; 1.0042x over previous
; __device__ __forceinline__ unsigned cvt_pk_bf16(float lo, float hi) { unsigned r; asm("v_cvt_pk_bf16_f32 %0, %1, %2" : "=v"(r) : "v"(lo), "v"(hi)); return r; }
; template <int DK, int DV, bool SEPQ> ...
;     ...
;         for (int vt = 0; vt < NVT; ++vt) { const f32x4 s = S[ct][vt]; u32x2 w; w.x = cvt_pk_bf16(s[0], s[1]); w.y = cvt_pk_bf16(s[2], s[3]);
;             *(u32x2*)(ST + (16 * vt + fr) * LQ + 16 * (wid * NCTW + ct) + 4 * fq) = w; }
;     __syncthreads();
; __device__ __forceinline__ void ret_block(ArgsP a_, unsigned char* smem) { const ArgsP a = a_;
;     ...
;         { const int cp = tid & 127, jq = tid >> 7;
;           float dj[16];
; #pragma unroll
;           for (int q4 = 0; q4 < 4; ++q4) { const f32x4 t = *(const f32x4*)(DECJ + 16 * jq + 4 * q4); dj[4 * q4] = t[0]; dj[4 * q4 + 1] = t[1]; dj[4 * q4 + 2] = t[2]; dj[4 * q4 + 3] = t[3]; }
;           unsigned lo[8], hi[8];
; #pragma unroll
;           for (int e = 0; e < 8; ++e) { const int j = 16 * jq + 2 * e; const unsigned w0 = *(const unsigned*)(KB + j * LQ + 2 * cp), w1 = *(const unsigned*)(KB + (j + 1) * LQ + 2 * cp);
;               lo[e] = cvt_pk_bf16(__uint_as_float(w0 << 16) * dj[2 * e], __uint_as_float(w1 << 16) * dj[2 * e + 1]);
;               hi[e] = cvt_pk_bf16(__uint_as_float(w0 & 0xffff0000u) * dj[2 * e], __uint_as_float(w1 & 0xffff0000u) * dj[2 * e + 1]); }
;           *(u32x4*)(KT + (2 * cp) * LJ + 16 * jq) = (u32x4){lo[0], lo[1], lo[2], lo[3]}; *(u32x4*)(KT + (2 * cp) * LJ + 16 * jq + 8) = (u32x4){lo[4], lo[5], lo[6], lo[7]};
;           *(u32x4*)(KT + (2 * cp + 1) * LJ + 16 * jq) = (u32x4){hi[0], hi[1], hi[2], hi[3]}; *(u32x4*)(KT + (2 * cp + 1) * LJ + 16 * jq + 8) = (u32x4){hi[4], hi[5], hi[6], hi[7]}; }
.LBB0_269:
	ds_read_b128 v[72:75], v142
	ds_read_b128 v[88:91], v142 offset:16
	ds_read_b128 v[84:87], v142 offset:32
	ds_read_b128 v[76:79], v142 offset:48
	ds_read_b32 v16, v140 offset:33792
	ds_read_b32 v18, v141 offset:34320
	s_waitcnt lgkmcnt(1)
	v_lshlrev_b32_e32 v19, 16, v16
	s_waitcnt lgkmcnt(0)
	v_lshlrev_b32_e32 v80, 16, v18
	v_and_b32_e32 v16, 0xffff0000, v16
	v_and_b32_e32 v18, 0xffff0000, v18
	v_mul_f32_e32 v16, v72, v16
	v_mul_f32_e32 v18, v73, v18
	v_mul_f32_e32 v19, v72, v19
	v_cvt_pk_bf16_f32 v72, v16, v18
	ds_read_b32 v16, v140 offset:34848
	ds_read_b32 v18, v141 offset:35376
	v_mul_f32_e32 v80, v73, v80
	v_cvt_pk_bf16_f32 v80, v19, v80
	s_waitcnt lgkmcnt(1)
	v_lshlrev_b32_e32 v19, 16, v16
	s_waitcnt lgkmcnt(0)
	v_lshlrev_b32_e32 v73, 16, v18
	v_and_b32_e32 v16, 0xffff0000, v16
	v_and_b32_e32 v18, 0xffff0000, v18
	v_mul_f32_e32 v73, v75, v73
	v_mul_f32_e32 v16, v74, v16
	v_mul_f32_e32 v18, v75, v18
	v_mul_f32_e32 v19, v74, v19
	v_cvt_pk_bf16_f32 v81, v19, v73
	v_cvt_pk_bf16_f32 v73, v16, v18
	ds_read_b32 v16, v140 offset:35904
	ds_read_b32 v18, v141 offset:36432
	s_waitcnt lgkmcnt(1)
	v_lshlrev_b32_e32 v19, 16, v16
	s_waitcnt lgkmcnt(0)
	v_lshlrev_b32_e32 v74, 16, v18
	v_and_b32_e32 v16, 0xffff0000, v16
	v_and_b32_e32 v18, 0xffff0000, v18
	v_mul_f32_e32 v74, v89, v74
	v_mul_f32_e32 v16, v88, v16
	v_mul_f32_e32 v18, v89, v18
	v_mul_f32_e32 v19, v88, v19
	v_cvt_pk_bf16_f32 v82, v19, v74
	v_cvt_pk_bf16_f32 v74, v16, v18
	ds_read_b32 v16, v140 offset:36960
	ds_read_b32 v18, v141 offset:37488
	s_waitcnt lgkmcnt(1)
	v_lshlrev_b32_e32 v19, 16, v16
	s_waitcnt lgkmcnt(0)
	v_lshlrev_b32_e32 v75, 16, v18
	v_and_b32_e32 v16, 0xffff0000, v16
	v_and_b32_e32 v18, 0xffff0000, v18
	v_mul_f32_e32 v75, v91, v75
	v_mul_f32_e32 v16, v90, v16
	v_mul_f32_e32 v18, v91, v18
	v_mul_f32_e32 v19, v90, v19
	v_cvt_pk_bf16_f32 v83, v19, v75
	v_cvt_pk_bf16_f32 v75, v16, v18
	ds_read_b32 v16, v140 offset:38016
	ds_read_b32 v18, v141 offset:38544
	s_waitcnt lgkmcnt(1)
	v_lshlrev_b32_e32 v19, 16, v16
	s_waitcnt lgkmcnt(0)
	v_lshlrev_b32_e32 v88, 16, v18
	v_and_b32_e32 v16, 0xffff0000, v16
	v_and_b32_e32 v18, 0xffff0000, v18
	v_mul_f32_e32 v16, v84, v16
	v_mul_f32_e32 v18, v85, v18
	v_mul_f32_e32 v19, v84, v19
	v_cvt_pk_bf16_f32 v84, v16, v18
	ds_read_b32 v16, v140 offset:39072
	ds_read_b32 v18, v141 offset:39600
	v_mul_f32_e32 v88, v85, v88
	v_cvt_pk_bf16_f32 v88, v19, v88
	s_waitcnt lgkmcnt(1)
	v_lshlrev_b32_e32 v19, 16, v16
	s_waitcnt lgkmcnt(0)
	v_lshlrev_b32_e32 v85, 16, v18
	v_and_b32_e32 v16, 0xffff0000, v16
	v_and_b32_e32 v18, 0xffff0000, v18
	v_mul_f32_e32 v85, v87, v85
	v_mul_f32_e32 v16, v86, v16
	v_mul_f32_e32 v18, v87, v18
	v_mul_f32_e32 v19, v86, v19
	v_cvt_pk_bf16_f32 v89, v19, v85
	v_cvt_pk_bf16_f32 v85, v16, v18
	ds_read_b32 v16, v140 offset:40128
	ds_read_b32 v18, v141 offset:40656
	s_waitcnt lgkmcnt(1)
	v_lshlrev_b32_e32 v19, 16, v16
	s_waitcnt lgkmcnt(0)
	v_lshlrev_b32_e32 v86, 16, v18
	v_and_b32_e32 v16, 0xffff0000, v16
	v_and_b32_e32 v18, 0xffff0000, v18
	v_mul_f32_e32 v86, v77, v86
	v_mul_f32_e32 v16, v76, v16
	v_mul_f32_e32 v18, v77, v18
	v_mul_f32_e32 v19, v76, v19
	v_cvt_pk_bf16_f32 v90, v19, v86
	v_cvt_pk_bf16_f32 v86, v16, v18
	ds_read_b32 v16, v140 offset:41184
	ds_read_b32 v18, v141 offset:41712
	v_cvt_pk_bf16_f32 v77, v54, v55
	s_waitcnt lgkmcnt(1)
	v_lshlrev_b32_e32 v19, 16, v16
	s_waitcnt lgkmcnt(0)
	v_lshlrev_b32_e32 v76, 16, v18
	v_and_b32_e32 v16, 0xffff0000, v16
	v_and_b32_e32 v18, 0xffff0000, v18
	v_mul_f32_e32 v19, v78, v19
	v_mul_f32_e32 v16, v78, v16
	v_mul_f32_e32 v18, v79, v18
	v_mul_f32_e32 v76, v79, v76
	v_cvt_pk_bf16_f32 v91, v19, v76
	v_cvt_pk_bf16_f32 v87, v16, v18
	v_cvt_pk_bf16_f32 v18, v40, v41
	v_cvt_pk_bf16_f32 v19, v42, v43
	v_add_u32_e32 v16, 0x2000, v143
	ds_write_b128 v124, v[80:83]
	ds_write_b128 v124, v[88:91] offset:16
	ds_write_b128 v124, v[72:75] offset:144
	ds_write_b128 v124, v[84:87] offset:160
	v_cvt_pk_bf16_f32 v72, v44, v45
	v_cvt_pk_bf16_f32 v73, v46, v47
	v_cvt_pk_bf16_f32 v78, v56, v57
	v_cvt_pk_bf16_f32 v79, v58, v59
	ds_write2_b64 v143, v[18:19], v[78:79] offset1:4
	v_cvt_pk_bf16_f32 v18, v60, v61
	v_cvt_pk_bf16_f32 v19, v62, v63
	ds_write2_b64 v16, v[72:73], v[18:19] offset0:32 offset1:36
	v_add_u32_e32 v16, 0x4000, v143
	v_cvt_pk_bf16_f32 v74, v48, v49
	v_cvt_pk_bf16_f32 v75, v50, v51
	v_cvt_pk_bf16_f32 v18, v64, v65
	v_cvt_pk_bf16_f32 v19, v66, v67
	ds_write2_b64 v16, v[74:75], v[18:19] offset0:64 offset1:68
	v_add_u32_e32 v16, 0x6000, v143
	v_cvt_pk_bf16_f32 v76, v52, v53
	v_cvt_pk_bf16_f32 v18, v68, v69
	v_cvt_pk_bf16_f32 v19, v70, v71
	ds_write2_b64 v16, v[76:77], v[18:19] offset0:96 offset1:100
	s_waitcnt lgkmcnt(0)
	s_barrier
; __device__ __forceinline__ unsigned cvt_pk_bf16(float lo, float hi) { unsigned r; asm("v_cvt_pk_bf16_f32 %0, %1, %2" : "=v"(r) : "v"(lo), "v"(hi)); return r; }
; template <int DK, int DV, bool SEPQ> ...
;     ...
;     {
;         const float gi_i = GI[16 * m + fr];
;         const int n0 = 2 * hw, n1 = 2 * hw + 1; const bool do0 = n0 <= m, do1 = n1 <= m;
;         f32x4 acc0 = {0.f, 0.f, 0.f, 0.f}, acc1 = {0.f, 0.f, 0.f, 0.f};
; #pragma unroll
;         for (int vt = 0; vt < NVTW; ++vt) O[vt] = (f32x4){0.f, 0.f, 0.f, 0.f};
; #pragma unroll
;         for (int ks = 0; ks < DK / 32; ++ks) {
;             const bf16x8 qf = *(const bf16x8*)(QA + (16 * m + fr) * LQ + 32 * ks + 8 * fq);
;             if (do0) { const bf16x8 kf = *(const bf16x8*)(KB + (16 * n0 + fr) * LQ + 32 * ks + 8 * fq); acc0 = __builtin_amdgcn_mfma_f32_16x16x32_bf16(kf, qf, acc0, 0, 0, 0); }
;             if (do1) { const bf16x8 kf = *(const bf16x8*)(KB + (16 * n1 + fr) * LQ + 32 * ks + 8 * fq); acc1 = __builtin_amdgcn_mfma_f32_16x16x32_bf16(kf, qf, acc1, 0, 0, 0); }
;             bf16x8 qs = qf; if (SEPQ) qs = *(const bf16x8*)(QS + (16 * m + fr) * LQ + 32 * ks + 8 * fq);
; #pragma unroll
;             for (int vt = 0; vt < NVTW; ++vt) { const bf16x8 sf = *(const bf16x8*)(ST + (16 * (hw * NVTW + vt) + fr) * LQ + 32 * ks + 8 * fq); O[vt] = __builtin_amdgcn_mfma_f32_16x16x32_bf16(sf, qs, O[vt], 0, 0, 0); }
;         }
; #pragma unroll
;         for (int nn = 0; nn < 2; ++nn) {
;             const int n = 2 * hw + nn; const f32x4 acc = nn == 0 ? acc0 : acc1;
;             const f32x4 gj = *(const f32x4*)(GI + 16 * n + 4 * fq); const int i = 16 * m + fr, j0 = 16 * n + 4 * fq; float p[4];
; #pragma unroll
;             for (int e = 0; e < 4; ++e) p[e] = (j0 + e <= i) ? acc[e] * __expf(gi_i - gj[e]) : 0.f;
;             u32x2 w; w.x = cvt_pk_bf16(p[0], p[1]); w.y = cvt_pk_bf16(p[2], p[3]); *(u32x2*)(P + (16 * m + fr) * LJ + j0) = w;
;         }
;         const float ei = __expf(gi_i);
; #pragma unroll
;         for (int vt = 0; vt < NVTW; ++vt) O[vt] = O[vt] * ei;
;     }
	ds_read_b32 v92, v125
	ds_read_b128 v[214:217], v126
	ds_read_b128 v[218:221], v127 offset:33792
	ds_read_b128 v[222:225], v127 offset:42240
	ds_read_b128 v[226:229], v165
	ds_read_b128 v[230:233], v165 offset:8448
	ds_read_b128 v[166:169], v126 offset:64
	ds_read_b128 v[170:173], v127 offset:33856
	ds_read_b128 v[174:177], v127 offset:42304
	ds_read_b128 v[178:181], v165 offset:64
	ds_read_b128 v[182:185], v165 offset:8512
	s_waitcnt lgkmcnt(5)
	v_mfma_f32_16x16x32_bf16 v[76:79], v[218:221], v[214:217], 0
	v_mfma_f32_16x16x32_bf16 v[72:75], v[222:225], v[214:217], 0
	v_mfma_f32_16x16x32_bf16 v[80:83], v[226:229], v[214:217], 0
	v_mfma_f32_16x16x32_bf16 v[84:87], v[230:233], v[214:217], 0
	ds_read_b128 v[214:217], v126 offset:128
	ds_read_b128 v[218:221], v127 offset:33920
	ds_read_b128 v[222:225], v127 offset:42368
	ds_read_b128 v[226:229], v165 offset:128
	ds_read_b128 v[230:233], v165 offset:8576
	s_waitcnt lgkmcnt(5)
	v_mfma_f32_16x16x32_bf16 v[76:79], v[170:173], v[166:169], v[76:79]
	v_mfma_f32_16x16x32_bf16 v[72:75], v[174:177], v[166:169], v[72:75]
	v_mfma_f32_16x16x32_bf16 v[80:83], v[178:181], v[166:169], v[80:83]
	v_mfma_f32_16x16x32_bf16 v[84:87], v[182:185], v[166:169], v[84:87]
	ds_read_b128 v[166:169], v126 offset:192
	ds_read_b128 v[170:173], v127 offset:33984
	ds_read_b128 v[174:177], v127 offset:42432
	ds_read_b128 v[178:181], v165 offset:192
	ds_read_b128 v[182:185], v165 offset:8640
	s_waitcnt lgkmcnt(5)
	v_mfma_f32_16x16x32_bf16 v[76:79], v[218:221], v[214:217], v[76:79]
	v_mfma_f32_16x16x32_bf16 v[72:75], v[222:225], v[214:217], v[72:75]
	v_mfma_f32_16x16x32_bf16 v[80:83], v[226:229], v[214:217], v[80:83]
	v_mfma_f32_16x16x32_bf16 v[84:87], v[230:233], v[214:217], v[84:87]
	ds_read_b128 v[214:217], v126 offset:256
	ds_read_b128 v[218:221], v127 offset:34048
	ds_read_b128 v[222:225], v127 offset:42496
	ds_read_b128 v[226:229], v165 offset:256
	ds_read_b128 v[230:233], v165 offset:8704
	s_waitcnt lgkmcnt(5)
	v_mfma_f32_16x16x32_bf16 v[76:79], v[170:173], v[166:169], v[76:79]
	v_mfma_f32_16x16x32_bf16 v[72:75], v[174:177], v[166:169], v[72:75]
	v_mfma_f32_16x16x32_bf16 v[80:83], v[178:181], v[166:169], v[80:83]
	v_mfma_f32_16x16x32_bf16 v[84:87], v[182:185], v[166:169], v[84:87]
	ds_read_b128 v[166:169], v126 offset:320
	ds_read_b128 v[170:173], v127 offset:34112
	ds_read_b128 v[174:177], v127 offset:42560
	ds_read_b128 v[178:181], v165 offset:320
	ds_read_b128 v[182:185], v165 offset:8768
	s_waitcnt lgkmcnt(5)
	v_mfma_f32_16x16x32_bf16 v[76:79], v[218:221], v[214:217], v[76:79]
	v_mfma_f32_16x16x32_bf16 v[72:75], v[222:225], v[214:217], v[72:75]
	v_mfma_f32_16x16x32_bf16 v[80:83], v[226:229], v[214:217], v[80:83]
	v_mfma_f32_16x16x32_bf16 v[84:87], v[230:233], v[214:217], v[84:87]
	ds_read_b128 v[214:217], v126 offset:384
	ds_read_b128 v[218:221], v127 offset:34176
	ds_read_b128 v[222:225], v127 offset:42624
	ds_read_b128 v[226:229], v165 offset:384
	ds_read_b128 v[230:233], v165 offset:8832
	s_waitcnt lgkmcnt(5)
	v_mfma_f32_16x16x32_bf16 v[76:79], v[170:173], v[166:169], v[76:79]
	v_mfma_f32_16x16x32_bf16 v[72:75], v[174:177], v[166:169], v[72:75]
	v_mfma_f32_16x16x32_bf16 v[80:83], v[178:181], v[166:169], v[80:83]
	v_mfma_f32_16x16x32_bf16 v[84:87], v[182:185], v[166:169], v[84:87]
	ds_read_b128 v[166:169], v126 offset:448
	ds_read_b128 v[170:173], v127 offset:34240
	ds_read_b128 v[174:177], v127 offset:42688
	ds_read_b128 v[178:181], v165 offset:448
	ds_read_b128 v[182:185], v165 offset:8896
	s_waitcnt lgkmcnt(5)
	v_mfma_f32_16x16x32_bf16 v[76:79], v[218:221], v[214:217], v[76:79]
	v_mfma_f32_16x16x32_bf16 v[72:75], v[222:225], v[214:217], v[72:75]
	v_mfma_f32_16x16x32_bf16 v[80:83], v[226:229], v[214:217], v[80:83]
	v_mfma_f32_16x16x32_bf16 v[84:87], v[230:233], v[214:217], v[84:87]
	s_waitcnt lgkmcnt(0)
	v_mfma_f32_16x16x32_bf16 v[76:79], v[170:173], v[166:169], v[76:79]
	v_mfma_f32_16x16x32_bf16 v[72:75], v[174:177], v[166:169], v[72:75]
	v_mfma_f32_16x16x32_bf16 v[80:83], v[178:181], v[166:169], v[80:83]
	v_mfma_f32_16x16x32_bf16 v[84:87], v[182:185], v[166:169], v[84:87]
	s_nop 7
	v_cmp_gt_i32_e32 vcc, s89, v132
	ds_read_b128 v[88:91], v128
	s_waitcnt lgkmcnt(0)
	v_sub_f32_e32 v16, v92, v88
	v_mul_f32_e32 v16, 0x3fb8aa3b, v16
	v_exp_f32_e32 v16, v16
	v_sub_f32_e32 v18, v92, v89
	v_sub_f32_e32 v19, v92, v90
	v_mul_f32_e32 v18, 0x3fb8aa3b, v18
	v_mul_f32_e32 v16, v76, v16
	v_mul_f32_e32 v19, 0x3fb8aa3b, v19
	v_sub_f32_e32 v76, v92, v91
	v_exp_f32_e32 v18, v18
	v_exp_f32_e32 v19, v19
	v_mul_f32_e32 v76, 0x3fb8aa3b, v76
	v_exp_f32_e32 v76, v76
	v_mul_f32_e32 v18, v77, v18
	v_mul_f32_e32 v19, v78, v19
	v_cndmask_b32_e64 v18, 0, v18, s[50:51]
	v_cndmask_b32_e64 v19, v19, 0, s[52:53]
	v_mul_f32_e32 v76, v79, v76
	v_cndmask_b32_e64 v16, v16, 0, s[48:49]
	v_cndmask_b32_e64 v76, v76, 0, s[54:55]
	v_cvt_pk_bf16_f32 v18, v16, v18
	v_cvt_pk_bf16_f32 v19, v19, v76
	ds_write_b64 v129, v[18:19]
	ds_read_b128 v[76:79], v128 offset:64
	s_waitcnt lgkmcnt(0)
	v_sub_f32_e32 v16, v92, v76
	v_mul_f32_e32 v16, 0x3fb8aa3b, v16
	v_sub_f32_e32 v18, v92, v77
	v_exp_f32_e32 v16, v16
	v_mul_f32_e32 v18, 0x3fb8aa3b, v18
	v_exp_f32_e32 v18, v18
	v_sub_f32_e32 v19, v92, v78
	v_mul_f32_e32 v16, v72, v16
	v_sub_f32_e32 v72, v92, v79
	v_mul_f32_e32 v18, v73, v18
	v_mul_f32_e32 v19, 0x3fb8aa3b, v19
	v_mul_f32_e32 v72, 0x3fb8aa3b, v72
	v_cndmask_b32_e64 v16, v16, 0, s[56:57]
	v_cndmask_b32_e64 v18, 0, v18, s[58:59]
	v_exp_f32_e32 v19, v19
	v_exp_f32_e32 v72, v72
	v_cvt_pk_bf16_f32 v18, v16, v18
	v_mul_f32_e32 v16, 0x3fb8aa3b, v92
	v_exp_f32_e32 v16, v16
	v_mul_f32_e32 v19, v74, v19
	v_mul_f32_e32 v72, v75, v72
	v_cndmask_b32_e64 v19, v19, 0, s[60:61]
	v_cndmask_b32_e64 v72, v72, 0, s[62:63]
	v_cvt_pk_bf16_f32 v19, v19, v72
	ds_write_b64 v129, v[18:19] offset:32
	v_pk_mul_f32 v[72:73], v[16:17], v[80:81] op_sel_hi:[0,1]
	v_pk_mul_f32 v[74:75], v[16:17], v[82:83] op_sel_hi:[0,1]
	v_pk_mul_f32 v[76:77], v[16:17], v[84:85] op_sel_hi:[0,1]
	v_pk_mul_f32 v[78:79], v[16:17], v[86:87] op_sel_hi:[0,1]
	s_waitcnt lgkmcnt(0)
	s_barrier
; __device__ __forceinline__ unsigned cvt_pk_bf16(float lo, float hi) { unsigned r; asm("v_cvt_pk_bf16_f32 %0, %1, %2" : "=v"(r) : "v"(lo), "v"(hi)); return r; }
; template <int DK, int DV, bool SEPQ> ...
;     ...
;     __syncthreads();
; #pragma unroll
;     for (int ks = 0; ks < 2; ++ks) { const bf16x8 pf = *(const bf16x8*)(P + (16 * m + fr) * LJ + 32 * ks + 8 * fq);
; #pragma unroll
;         for (int vt = 0; vt < NVTW; ++vt) { const bf16x8 vf = *(const bf16x8*)(VT + (16 * (hw * NVTW + vt) + fr) * LJ + 32 * ks + 8 * fq); O[vt] = __builtin_amdgcn_mfma_f32_16x16x32_bf16(vf, pf, O[vt], 0, 0, 0); } }
; #pragma unroll
;     for (int ct = 0; ct < NCTW; ++ct) { const int ctg = wid * NCTW + ct; const f32x4 dec = *(const f32x4*)(SDEC + 16 * ctg + 4 * fq);
; #pragma unroll
;         for (int vt = 0; vt < NVT; ++vt) S[ct][vt] = S[ct][vt] * dec;
; #pragma unroll
;         for (int ks = 0; ks < 2; ++ks) { const bf16x8 kf = *(const bf16x8*)(KT + (16 * ctg + fr) * LJ + 32 * ks + 8 * fq);
; #pragma unroll
;             for (int vt = 0; vt < NVT; ++vt) { const bf16x8 vf = *(const bf16x8*)(VT2 + (16 * vt + fr) * LJ + 32 * ks + 8 * fq); S[ct][vt] = __builtin_amdgcn_mfma_f32_16x16x32_bf16(kf, vf, S[ct][vt], 0, 0, 0); } } }
; __device__ __forceinline__ void ret_block(ArgsP a_, unsigned char* smem) { const ArgsP a = a_;
;     ...
;         const int m = wid >> 1, hw = wid & 1, i = 16 * m + fr;
;         if (i < len) {
; #pragma unroll
;             for (int vt = 0; vt < 2; ++vt) *(u32x2*)(OB + (size_t)(row0 + i) * 2048 + h * 512 + vs * 64 + 16 * (hw * 2 + vt) + 4 * fq) = (u32x2){cvt_pk_bf16(O[vt][0], O[vt][1]), cvt_pk_bf16(O[vt][2], O[vt][3])}; }
	ds_read_b128 v[80:83], v130
	ds_read_b128 v[84:87], v144
	s_waitcnt lgkmcnt(0)
	v_mfma_f32_16x16x32_bf16 v[72:75], v[84:87], v[80:83], v[72:75]
	ds_read_b128 v[84:87], v144 offset:2304
	s_waitcnt lgkmcnt(0)
	v_mfma_f32_16x16x32_bf16 v[76:79], v[84:87], v[80:83], v[76:79]
	ds_read_b128 v[80:83], v130 offset:64
	ds_read_b128 v[84:87], v144 offset:64
	s_waitcnt lgkmcnt(0)
	v_mfma_f32_16x16x32_bf16 v[72:75], v[84:87], v[80:83], v[72:75]
	ds_read_b128 v[84:87], v144 offset:2368
	s_waitcnt lgkmcnt(0)
	v_mfma_f32_16x16x32_bf16 v[76:79], v[84:87], v[80:83], v[76:79]
	ds_read_b128 v[80:83], v131
	s_waitcnt lgkmcnt(0)
	v_pk_mul_f32 v[42:43], v[42:43], v[82:83]
	v_pk_mul_f32 v[40:41], v[40:41], v[80:81]
	v_pk_mul_f32 v[46:47], v[46:47], v[82:83]
	v_pk_mul_f32 v[44:45], v[44:45], v[80:81]
	v_pk_mul_f32 v[50:51], v[50:51], v[82:83]
	v_pk_mul_f32 v[48:49], v[48:49], v[80:81]
	v_pk_mul_f32 v[54:55], v[54:55], v[82:83]
	v_pk_mul_f32 v[52:53], v[52:53], v[80:81]
	ds_read_b128 v[80:83], v145
	ds_read_b128 v[166:169], v147
	ds_read_b128 v[170:173], v147 offset:2304
	ds_read_b128 v[174:177], v147 offset:4608
	ds_read_b128 v[178:181], v147 offset:6912
	s_waitcnt lgkmcnt(3)
	v_mfma_f32_16x16x32_bf16 v[40:43], v[80:83], v[166:169], v[40:43]
	s_waitcnt lgkmcnt(2)
	v_mfma_f32_16x16x32_bf16 v[44:47], v[80:83], v[170:173], v[44:47]
	s_waitcnt lgkmcnt(1)
	v_mfma_f32_16x16x32_bf16 v[48:51], v[80:83], v[174:177], v[48:51]
	s_waitcnt lgkmcnt(0)
	v_mfma_f32_16x16x32_bf16 v[52:55], v[80:83], v[178:181], v[52:55]
	ds_read_b128 v[182:185], v145 offset:64
	ds_read_b128 v[80:83], v147 offset:64
	ds_read_b128 v[84:87], v147 offset:2368
	ds_read_b128 v[88:91], v147 offset:4672
	ds_read_b128 v[92:95], v147 offset:6976
	s_waitcnt lgkmcnt(3)
	v_mfma_f32_16x16x32_bf16 v[40:43], v[182:185], v[80:83], v[40:43]
	s_waitcnt lgkmcnt(2)
	v_mfma_f32_16x16x32_bf16 v[44:47], v[182:185], v[84:87], v[44:47]
	s_waitcnt lgkmcnt(1)
	v_mfma_f32_16x16x32_bf16 v[48:51], v[182:185], v[88:91], v[48:51]
	s_waitcnt lgkmcnt(0)
	v_mfma_f32_16x16x32_bf16 v[52:55], v[182:185], v[92:95], v[52:55]
	ds_read_b128 v[182:185], v131 offset:64
	s_waitcnt lgkmcnt(0)
	v_pk_mul_f32 v[58:59], v[58:59], v[184:185]
	v_pk_mul_f32 v[56:57], v[56:57], v[182:183]
	v_pk_mul_f32 v[62:63], v[62:63], v[184:185]
	v_pk_mul_f32 v[60:61], v[60:61], v[182:183]
	v_pk_mul_f32 v[66:67], v[66:67], v[184:185]
	v_pk_mul_f32 v[64:65], v[64:65], v[182:183]
	v_pk_mul_f32 v[70:71], v[70:71], v[184:185]
	v_pk_mul_f32 v[68:69], v[68:69], v[182:183]
	ds_read_b128 v[182:185], v164
	s_waitcnt lgkmcnt(0)
	v_mfma_f32_16x16x32_bf16 v[56:59], v[182:185], v[166:169], v[56:59]
	ds_read_b128 v[166:169], v164 offset:64
	v_mfma_f32_16x16x32_bf16 v[60:63], v[182:185], v[170:173], v[60:63]
	v_mfma_f32_16x16x32_bf16 v[64:67], v[182:185], v[174:177], v[64:67]
	v_mfma_f32_16x16x32_bf16 v[68:71], v[182:185], v[178:181], v[68:71]
	s_waitcnt lgkmcnt(0)
	v_mfma_f32_16x16x32_bf16 v[56:59], v[166:169], v[80:83], v[56:59]
	v_mfma_f32_16x16x32_bf16 v[60:63], v[166:169], v[84:87], v[60:63]
	v_mfma_f32_16x16x32_bf16 v[64:67], v[166:169], v[88:91], v[64:67]
	v_mfma_f32_16x16x32_bf16 v[68:71], v[166:169], v[92:95], v[68:71]
	s_and_saveexec_b64 s[64:65], vcc
	s_cbranch_execz .LBB0_303
	v_add_u32_e32 v18, s88, v132
	v_ashrrev_i32_e32 v19, 31, v18
	v_lshlrev_b64 v[18:19], 12, v[18:19]
	v_lshl_add_u64 v[18:19], s[26:27], 0, v[18:19]
	s_lshl_b32 s70, s91, 10
	s_mov_b32 s71, s12
	v_lshl_add_u64 v[18:19], v[18:19], 0, s[70:71]
	s_lshl_b32 s70, s90, 7
	v_lshl_add_u64 v[18:19], v[18:19], 0, s[70:71]
	v_mov_b32_e32 v113, v17
	v_lshl_add_u64 v[18:19], v[18:19], 0, v[112:113]
	v_mov_b32_e32 v115, v17
	v_cvt_pk_bf16_f32 v72, v72, v73
	v_cvt_pk_bf16_f32 v73, v74, v75
	v_lshl_add_u64 v[18:19], v[18:19], 0, v[114:115]
	global_store_dwordx2 v[18:19], v[72:73], off
	v_cvt_pk_bf16_f32 v72, v76, v77
	v_cvt_pk_bf16_f32 v73, v78, v79
	global_store_dwordx2 v[18:19], v[72:73], off offset:32

; template <int DK, int DV, bool SEPQ> ...
;     ...
;     {
;         const float gi_i = GI[16 * m + fr];
;         const int n0 = 2 * hw, n1 = 2 * hw + 1; const bool do0 = n0 <= m, do1 = n1 <= m;
;         f32x4 acc0 = {0.f, 0.f, 0.f, 0.f}, acc1 = {0.f, 0.f, 0.f, 0.f};
; #pragma unroll
;         for (int vt = 0; vt < NVTW; ++vt) O[vt] = (f32x4){0.f, 0.f, 0.f, 0.f};
; #pragma unroll
;         for (int ks = 0; ks < DK / 32; ++ks) {
;             const bf16x8 qf = *(const bf16x8*)(QA + (16 * m + fr) * LQ + 32 * ks + 8 * fq);
;             if (do0) { const bf16x8 kf = *(const bf16x8*)(KB + (16 * n0 + fr) * LQ + 32 * ks + 8 * fq); acc0 = __builtin_amdgcn_mfma_f32_16x16x32_bf16(kf, qf, acc0, 0, 0, 0); }
;             if (do1) { const bf16x8 kf = *(const bf16x8*)(KB + (16 * n1 + fr) * LQ + 32 * ks + 8 * fq); acc1 = __builtin_amdgcn_mfma_f32_16x16x32_bf16(kf, qf, acc1, 0, 0, 0); }
;             bf16x8 qs = qf; if (SEPQ) qs = *(const bf16x8*)(QS + (16 * m + fr) * LQ + 32 * ks + 8 * fq);
; #pragma unroll
;             for (int vt = 0; vt < NVTW; ++vt) { const bf16x8 sf = *(const bf16x8*)(ST + (16 * (hw * NVTW + vt) + fr) * LQ + 32 * ks + 8 * fq); O[vt] = __builtin_amdgcn_mfma_f32_16x16x32_bf16(sf, qs, O[vt], 0, 0, 0); }
;         }
; #pragma unroll
;         for (int nn = 0; nn < 2; ++nn) {
;             const int n = 2 * hw + nn; const f32x4 acc = nn == 0 ? acc0 : acc1;
;             const f32x4 gj = *(const f32x4*)(GI + 16 * n + 4 * fq); const int i = 16 * m + fr, j0 = 16 * n + 4 * fq; float p[4];
; #pragma unroll
;             for (int e = 0; e < 4; ++e) p[e] = (j0 + e <= i) ? acc[e] * __expf(gi_i - gj[e]) : 0.f;
;             u32x2 w; w.x = cvt_pk_bf16(p[0], p[1]); w.y = cvt_pk_bf16(p[2], p[3]); *(u32x2*)(P + (16 * m + fr) * LJ + j0) = w;
;         }
;         const float ei = __expf(gi_i);
; #pragma unroll
;         for (int vt = 0; vt < NVTW; ++vt) O[vt] = O[vt] * ei;
;     }
; __device__ __forceinline__ void mamba_block(ArgsP a_, unsigned char* smem) { const ArgsP a = a_;
;     ...
;         if (i < len) { const float Dh = AIN(24)[hd];
; #pragma unroll
;             for (int vt = 0; vt < 2; ++vt) { const int v = 16 * (hw * 2 + vt) + 4 * fq; const size_t o = (size_t)(row0 + i) * 2048 + hd * 64 + v;
;                 const u32x2 xt = *(const u32x2*)(XC + (size_t)(row0 + i) * 4096 + hd * 64 + v); const u32x2 zt = *(const u32x2*)(ZG + o);
.LBB0_356:
	s_load_dwordx2 s[22:23], s[4:5], 0xc0
	v_add_u32_e32 v212, s72, v71
	v_ashrrev_i32_e32 v213, 31, v212
	v_lshlrev_b64 v[214:215], 11, v[212:213]
	v_lshlrev_b64 v[212:213], 13, v[212:213]
	v_readlane_b32 s74, v255, 12
	v_readlane_b32 s75, v255, 13
	v_lshl_or_b32 v216, s71, 6, v214
	v_or_b32_e32 v214, v216, v66
	s_nop 0
	v_lshl_add_u64 v[212:213], s[74:75], 0, v[212:213]
	s_lshl_b32 s74, s71, 7
	s_mov_b32 s75, s12
	v_lshl_add_u64 v[212:213], v[212:213], 0, s[74:75]
	v_lshlrev_b32_e32 v218, 1, v66
	v_mov_b32_e32 v219, 0
	v_lshl_add_u64 v[212:213], v[212:213], 0, v[218:219]
	v_lshlrev_b64 v[218:219], 1, v[214:215]
	global_load_dwordx2 v[202:203], v[212:213], off
	v_lshl_add_u64 v[218:219], s[24:25], 0, v[218:219]
	global_load_dwordx2 v[204:205], v[218:219], off
	global_load_dwordx2 v[206:207], v[212:213], off offset:32
	v_or_b32_e32 v214, v216, v68
	v_lshlrev_b64 v[218:219], 1, v[214:215]
	v_lshl_add_u64 v[218:219], s[24:25], 0, v[218:219]
	global_load_dwordx2 v[208:209], v[218:219], off
	s_lshl_b32 s74, s71, 2
	v_mov_b32_e32 v217, s74
	s_waitcnt lgkmcnt(0)
	global_load_dword v210, v217, s[22:23]
	v_cvt_pk_bf16_f32 v18, v20, v21
	v_cvt_pk_bf16_f32 v19, v22, v23
	ds_write_b64 v109, v[18:19]
	v_cvt_pk_bf16_f32 v18, v24, v25
	v_cvt_pk_bf16_f32 v19, v26, v27
	ds_write_b64 v109, v[18:19] offset:4352
	v_cvt_pk_bf16_f32 v18, v28, v29
	v_cvt_pk_bf16_f32 v19, v30, v31
	ds_write_b64 v109, v[18:19] offset:8704
	v_cvt_pk_bf16_f32 v18, v32, v33
	v_cvt_pk_bf16_f32 v19, v34, v35
	ds_write_b64 v109, v[18:19] offset:13056
	s_waitcnt lgkmcnt(0)
	s_barrier
	ds_read_b32 v123, v81
	ds_read_b128 v[220:223], v64
	ds_read_b128 v[224:227], v65 offset:17408
	ds_read_b128 v[228:231], v65 offset:21760
	ds_read_b128 v[232:235], v114
	ds_read_b128 v[236:239], v114 offset:4352
	ds_read_b128 v[164:167], v64 offset:64
	ds_read_b128 v[168:171], v65 offset:17472
	ds_read_b128 v[172:175], v65 offset:21824
	ds_read_b128 v[176:179], v114 offset:64
	ds_read_b128 v[180:183], v114 offset:4416
	s_waitcnt lgkmcnt(5)
	v_mfma_f32_16x16x32_bf16 v[40:43], v[224:227], v[220:223], 0
	v_mfma_f32_16x16x32_bf16 v[36:39], v[228:231], v[220:223], 0
	v_mfma_f32_16x16x32_bf16 v[44:47], v[232:235], v[220:223], 0
	v_mfma_f32_16x16x32_bf16 v[48:51], v[236:239], v[220:223], 0
	ds_read_b128 v[220:223], v64 offset:128
	ds_read_b128 v[224:227], v65 offset:17536
	ds_read_b128 v[228:231], v65 offset:21888
	ds_read_b128 v[232:235], v114 offset:128
	ds_read_b128 v[236:239], v114 offset:4480
	s_waitcnt lgkmcnt(5)
	v_mfma_f32_16x16x32_bf16 v[40:43], v[168:171], v[164:167], v[40:43]
	v_mfma_f32_16x16x32_bf16 v[36:39], v[172:175], v[164:167], v[36:39]
	v_mfma_f32_16x16x32_bf16 v[44:47], v[176:179], v[164:167], v[44:47]
	v_mfma_f32_16x16x32_bf16 v[48:51], v[180:183], v[164:167], v[48:51]
	ds_read_b128 v[164:167], v64 offset:192
	ds_read_b128 v[168:171], v65 offset:17600
	ds_read_b128 v[172:175], v65 offset:21952
	ds_read_b128 v[176:179], v114 offset:192
	ds_read_b128 v[180:183], v114 offset:4544
	s_waitcnt lgkmcnt(5)
	v_mfma_f32_16x16x32_bf16 v[40:43], v[224:227], v[220:223], v[40:43]
	v_mfma_f32_16x16x32_bf16 v[36:39], v[228:231], v[220:223], v[36:39]
	v_mfma_f32_16x16x32_bf16 v[44:47], v[232:235], v[220:223], v[44:47]
	v_mfma_f32_16x16x32_bf16 v[48:51], v[236:239], v[220:223], v[48:51]
	s_waitcnt lgkmcnt(0)
	v_mfma_f32_16x16x32_bf16 v[40:43], v[168:171], v[164:167], v[40:43]
	v_mfma_f32_16x16x32_bf16 v[36:39], v[172:175], v[164:167], v[36:39]
	v_mfma_f32_16x16x32_bf16 v[44:47], v[176:179], v[164:167], v[44:47]
	v_mfma_f32_16x16x32_bf16 v[48:51], v[180:183], v[164:167], v[48:51]
	s_nop 7
	v_cmp_gt_i32_e32 vcc, s73, v71
	ds_read_b128 v[52:55], v82
	s_waitcnt lgkmcnt(0)
	v_sub_f32_e32 v16, v123, v52
	v_mul_f32_e32 v16, 0x3fb8aa3b, v16
	v_exp_f32_e32 v16, v16
	v_sub_f32_e32 v18, v123, v53
	v_sub_f32_e32 v19, v123, v54
	v_mul_f32_e32 v18, 0x3fb8aa3b, v18
	v_mul_f32_e32 v16, v40, v16
	v_mul_f32_e32 v19, 0x3fb8aa3b, v19
	v_sub_f32_e32 v40, v123, v55
	v_exp_f32_e32 v18, v18
	v_exp_f32_e32 v19, v19
	v_mul_f32_e32 v40, 0x3fb8aa3b, v40
	v_exp_f32_e32 v40, v40
	v_mul_f32_e32 v18, v41, v18
	v_mul_f32_e32 v19, v42, v19
	v_cndmask_b32_e64 v18, 0, v18, s[48:49]
	v_cndmask_b32_e64 v19, v19, 0, s[50:51]
	v_mul_f32_e32 v40, v43, v40
	v_cndmask_b32_e64 v16, v16, 0, s[46:47]
	v_cndmask_b32_e64 v40, v40, 0, s[52:53]
	v_cvt_pk_bf16_f32 v18, v16, v18
	v_cvt_pk_bf16_f32 v19, v19, v40
	ds_write_b64 v83, v[18:19]
	ds_read_b128 v[40:43], v82 offset:64
	s_waitcnt lgkmcnt(0)
	v_sub_f32_e32 v16, v123, v40
	v_mul_f32_e32 v16, 0x3fb8aa3b, v16
	v_sub_f32_e32 v18, v123, v41
	v_exp_f32_e32 v16, v16
	v_mul_f32_e32 v18, 0x3fb8aa3b, v18
	v_exp_f32_e32 v18, v18
	v_sub_f32_e32 v19, v123, v42
	v_mul_f32_e32 v16, v36, v16
	v_sub_f32_e32 v36, v123, v43
	v_mul_f32_e32 v18, v37, v18
	v_mul_f32_e32 v19, 0x3fb8aa3b, v19
	v_mul_f32_e32 v36, 0x3fb8aa3b, v36
	v_cndmask_b32_e64 v16, v16, 0, s[54:55]
	v_cndmask_b32_e64 v18, 0, v18, s[56:57]
	v_exp_f32_e32 v19, v19
	v_exp_f32_e32 v36, v36
	v_cvt_pk_bf16_f32 v18, v16, v18
	v_mul_f32_e32 v16, 0x3fb8aa3b, v123
	v_exp_f32_e32 v16, v16
	v_mul_f32_e32 v19, v38, v19
	v_mul_f32_e32 v36, v39, v36
	v_cndmask_b32_e64 v19, v19, 0, s[58:59]
	v_cndmask_b32_e64 v36, v36, 0, s[60:61]
	v_cvt_pk_bf16_f32 v19, v19, v36
	ds_write_b64 v83, v[18:19] offset:32
	v_pk_mul_f32 v[36:37], v[16:17], v[44:45] op_sel_hi:[0,1]
	v_pk_mul_f32 v[38:39], v[16:17], v[46:47] op_sel_hi:[0,1]
	v_pk_mul_f32 v[40:41], v[16:17], v[48:49] op_sel_hi:[0,1]
	v_pk_mul_f32 v[42:43], v[16:17], v[50:51] op_sel_hi:[0,1]
	s_waitcnt lgkmcnt(0)
	s_barrier
; __device__ __forceinline__ unsigned cvt_pk_bf16(float lo, float hi) { unsigned r; asm("v_cvt_pk_bf16_f32 %0, %1, %2" : "=v"(r) : "v"(lo), "v"(hi)); return r; }
; template <int DK, int DV, bool SEPQ> ...
;     ...
;     __syncthreads();
; #pragma unroll
;     for (int ks = 0; ks < 2; ++ks) { const bf16x8 pf = *(const bf16x8*)(P + (16 * m + fr) * LJ + 32 * ks + 8 * fq);
; #pragma unroll
;         for (int vt = 0; vt < NVTW; ++vt) { const bf16x8 vf = *(const bf16x8*)(VT + (16 * (hw * NVTW + vt) + fr) * LJ + 32 * ks + 8 * fq); O[vt] = __builtin_amdgcn_mfma_f32_16x16x32_bf16(vf, pf, O[vt], 0, 0, 0); } }
; #pragma unroll
;     for (int ct = 0; ct < NCTW; ++ct) { const int ctg = wid * NCTW + ct; const f32x4 dec = *(const f32x4*)(SDEC + 16 * ctg + 4 * fq);
; #pragma unroll
;         for (int vt = 0; vt < NVT; ++vt) S[ct][vt] = S[ct][vt] * dec;
; #pragma unroll
;         for (int ks = 0; ks < 2; ++ks) { const bf16x8 kf = *(const bf16x8*)(KT + (16 * ctg + fr) * LJ + 32 * ks + 8 * fq);
; #pragma unroll
;             for (int vt = 0; vt < NVT; ++vt) { const bf16x8 vf = *(const bf16x8*)(VT2 + (16 * vt + fr) * LJ + 32 * ks + 8 * fq); S[ct][vt] = __builtin_amdgcn_mfma_f32_16x16x32_bf16(kf, vf, S[ct][vt], 0, 0, 0); } } }
; __device__ __forceinline__ void mamba_block(ArgsP a_, unsigned char* smem) { const ArgsP a = a_;
;     ...
;         const int m = wid >> 1, hw = wid & 1, i = 16 * m + fr;
;         if (i < len) { const float Dh = AIN(24)[hd];
; #pragma unroll
;             for (int vt = 0; vt < 2; ++vt) { const int v = 16 * (hw * 2 + vt) + 4 * fq; const size_t o = (size_t)(row0 + i) * 2048 + hd * 64 + v;
;                 const u32x2 xt = *(const u32x2*)(XC + (size_t)(row0 + i) * 4096 + hd * 64 + v); const u32x2 zt = *(const u32x2*)(ZG + o);
;                 const f32x4 xs = {__uint_as_float(xt.x << 16), __uint_as_float(xt.x & 0xffff0000u), __uint_as_float(xt.y << 16), __uint_as_float(xt.y & 0xffff0000u)};
;                 const f32x4 zg = {__uint_as_float(zt.x << 16), __uint_as_float(zt.x & 0xffff0000u), __uint_as_float(zt.y << 16), __uint_as_float(zt.y & 0xffff0000u)};
;                 const f32x4 y = (O[vt] + xs * Dh) * zg; *(u32x2*)(YB + o) = (u32x2){cvt_pk_bf16(y[0], y[1]), cvt_pk_bf16(y[2], y[3])}; } }
	ds_read_b128 v[44:47], v84
	ds_read_b128 v[48:51], v110 offset:53248
	s_waitcnt lgkmcnt(0)
	v_mfma_f32_16x16x32_bf16 v[36:39], v[48:51], v[44:47], v[36:39]
	ds_read_b128 v[48:51], v110 offset:55552
	s_waitcnt lgkmcnt(0)
	v_mfma_f32_16x16x32_bf16 v[44:47], v[48:51], v[44:47], v[40:43]
	ds_read_b128 v[48:51], v84 offset:64
	s_nop 1
	ds_read_b128 v[40:43], v110 offset:53312
	s_waitcnt lgkmcnt(0)
	v_mfma_f32_16x16x32_bf16 v[40:43], v[40:43], v[48:51], v[36:39]
	s_nop 2
	ds_read_b128 v[36:39], v110 offset:55616
	s_waitcnt lgkmcnt(0)
	v_mfma_f32_16x16x32_bf16 v[36:39], v[36:39], v[48:51], v[44:47]
	s_nop 2
	ds_read_b128 v[44:47], v111
	s_waitcnt lgkmcnt(0)
	v_pk_mul_f32 v[22:23], v[22:23], v[46:47]
	v_pk_mul_f32 v[20:21], v[20:21], v[44:45]
	v_pk_mul_f32 v[24:25], v[24:25], v[44:45]
	v_pk_mul_f32 v[26:27], v[26:27], v[46:47]
	v_pk_mul_f32 v[28:29], v[28:29], v[44:45]
	v_pk_mul_f32 v[30:31], v[30:31], v[46:47]
	v_pk_mul_f32 v[32:33], v[32:33], v[44:45]
	v_pk_mul_f32 v[34:35], v[34:35], v[46:47]
	ds_read_b128 v[44:47], v70 offset:34816
	ds_read_b128 v[48:51], v112 offset:62464
	s_waitcnt lgkmcnt(0)
	v_mfma_f32_16x16x32_bf16 v[18:21], v[44:47], v[48:51], v[20:23]
	ds_read_b128 v[48:51], v112 offset:64768
	s_waitcnt lgkmcnt(0)
	v_mfma_f32_16x16x32_bf16 v[24:27], v[44:47], v[48:51], v[24:27]
	ds_read_b128 v[48:51], v113 offset:62464
	s_waitcnt lgkmcnt(0)
	v_mfma_f32_16x16x32_bf16 v[28:31], v[44:47], v[48:51], v[28:31]
	ds_read_b128 v[48:51], v113 offset:64768
	s_waitcnt lgkmcnt(0)
	v_mfma_f32_16x16x32_bf16 v[32:35], v[44:47], v[48:51], v[32:35]
	ds_read_b128 v[44:47], v70 offset:34880
	ds_read_b128 v[48:51], v112 offset:62528
	s_waitcnt lgkmcnt(0)
	v_mfma_f32_16x16x32_bf16 v[20:23], v[44:47], v[48:51], v[18:21]
	ds_read_b128 v[48:51], v112 offset:64832
	s_waitcnt lgkmcnt(0)
	v_mfma_f32_16x16x32_bf16 v[24:27], v[44:47], v[48:51], v[24:27]
	ds_read_b128 v[48:51], v113 offset:62528
	s_waitcnt lgkmcnt(0)
	v_mfma_f32_16x16x32_bf16 v[28:31], v[44:47], v[48:51], v[28:31]
	ds_read_b128 v[48:51], v113 offset:64832
	s_waitcnt lgkmcnt(0)
	v_mfma_f32_16x16x32_bf16 v[32:35], v[44:47], v[48:51], v[32:35]
	s_and_saveexec_b64 s[74:75], vcc
	s_cbranch_execz .LBB0_374
	v_add_u32_e32 v44, s72, v71
	v_ashrrev_i32_e32 v45, 31, v44
	s_waitcnt vmcnt(0)
	v_mov_b32_e32 v18, v210
	v_readlane_b32 s22, v255, 12
	v_lshlrev_b64 v[46:47], 11, v[44:45]
	v_lshlrev_b64 v[44:45], 13, v[44:45]
	v_readlane_b32 s23, v255, 13
	v_lshl_or_b32 v19, s71, 6, v46
	v_or_b32_e32 v46, v19, v66
	v_lshl_add_u64 v[44:45], s[22:23], 0, v[44:45]
	s_lshl_b32 s22, s71, 7
	s_mov_b32 s23, s12
	v_lshl_add_u64 v[44:45], v[44:45], 0, s[22:23]
	v_lshlrev_b32_e32 v16, 1, v66
	v_lshl_add_u64 v[44:45], v[44:45], 0, v[16:17]
	v_lshlrev_b64 v[50:51], 1, v[46:47]
	v_mov_b32_e32 v48, v202
	v_mov_b32_e32 v49, v203
	v_lshl_add_u64 v[52:53], s[24:25], 0, v[50:51]
	v_mov_b32_e32 v52, v204
	v_mov_b32_e32 v53, v205
	v_or_b32_e32 v46, v19, v68
	v_lshlrev_b32_e32 v54, 16, v48
	v_and_b32_e32 v55, 0xffff0000, v48
	v_lshlrev_b32_e32 v48, 16, v49
	v_and_b32_e32 v49, 0xffff0000, v49
	v_lshlrev_b32_e32 v124, 16, v52
	v_and_b32_e32 v125, 0xffff0000, v52
	v_lshlrev_b32_e32 v52, 16, v53
	v_and_b32_e32 v53, 0xffff0000, v53
	v_pk_fma_f32 v[40:41], v[18:19], v[54:55], v[40:41] op_sel_hi:[0,1,1]
	v_pk_fma_f32 v[42:43], v[18:19], v[48:49], v[42:43] op_sel_hi:[0,1,1]
	v_pk_mul_f32 v[42:43], v[42:43], v[52:53]
	v_pk_mul_f32 v[40:41], v[40:41], v[124:125]
	s_nop 0
	v_cvt_pk_bf16_f32 v40, v40, v41
	v_cvt_pk_bf16_f32 v41, v42, v43
	v_lshl_add_u64 v[42:43], s[26:27], 0, v[50:51]
	global_store_dwordx2 v[42:43], v[40:41], off
	v_lshlrev_b64 v[42:43], 1, v[46:47]
	v_mov_b32_e32 v40, v206
	v_mov_b32_e32 v41, v207
	v_lshl_add_u64 v[44:45], s[24:25], 0, v[42:43]
	v_mov_b32_e32 v44, v208
	v_mov_b32_e32 v45, v209
	v_lshlrev_b32_e32 v46, 16, v40
	v_and_b32_e32 v47, 0xffff0000, v40
	v_lshlrev_b32_e32 v40, 16, v41
	v_and_b32_e32 v41, 0xffff0000, v41
	v_lshlrev_b32_e32 v48, 16, v44
	v_and_b32_e32 v49, 0xffff0000, v44
	v_lshlrev_b32_e32 v44, 16, v45
	v_and_b32_e32 v45, 0xffff0000, v45
	v_pk_fma_f32 v[36:37], v[18:19], v[46:47], v[36:37] op_sel_hi:[0,1,1]
	v_pk_fma_f32 v[18:19], v[18:19], v[40:41], v[38:39] op_sel_hi:[0,1,1]
	v_pk_mul_f32 v[18:19], v[18:19], v[44:45]
	v_pk_mul_f32 v[36:37], v[36:37], v[48:49]
	s_nop 0
	v_cvt_pk_bf16_f32 v36, v36, v37
	v_cvt_pk_bf16_f32 v37, v18, v19
	v_lshl_add_u64 v[18:19], s[26:27], 0, v[42:43]
	global_store_dwordx2 v[18:19], v[36:37], off

; __device__ __forceinline__ unsigned cvt_pk_bf16(float lo, float hi) { unsigned r; asm("v_cvt_pk_bf16_f32 %0, %1, %2" : "=v"(r) : "v"(lo), "v"(hi)); return r; }
; template <int DK, int DV, bool SEPQ> ...
;     ...
;     {
;         const float gi_i = GI[16 * m + fr];
;         const int n0 = 2 * hw, n1 = 2 * hw + 1; const bool do0 = n0 <= m, do1 = n1 <= m;
;         f32x4 acc0 = {0.f, 0.f, 0.f, 0.f}, acc1 = {0.f, 0.f, 0.f, 0.f};
; #pragma unroll
;         for (int vt = 0; vt < NVTW; ++vt) O[vt] = (f32x4){0.f, 0.f, 0.f, 0.f};
; #pragma unroll
;         for (int ks = 0; ks < DK / 32; ++ks) {
;             const bf16x8 qf = *(const bf16x8*)(QA + (16 * m + fr) * LQ + 32 * ks + 8 * fq);
;             if (do0) { const bf16x8 kf = *(const bf16x8*)(KB + (16 * n0 + fr) * LQ + 32 * ks + 8 * fq); acc0 = __builtin_amdgcn_mfma_f32_16x16x32_bf16(kf, qf, acc0, 0, 0, 0); }
;             if (do1) { const bf16x8 kf = *(const bf16x8*)(KB + (16 * n1 + fr) * LQ + 32 * ks + 8 * fq); acc1 = __builtin_amdgcn_mfma_f32_16x16x32_bf16(kf, qf, acc1, 0, 0, 0); }
;             bf16x8 qs = qf; if (SEPQ) qs = *(const bf16x8*)(QS + (16 * m + fr) * LQ + 32 * ks + 8 * fq);
; #pragma unroll
;             for (int vt = 0; vt < NVTW; ++vt) { const bf16x8 sf = *(const bf16x8*)(ST + (16 * (hw * NVTW + vt) + fr) * LQ + 32 * ks + 8 * fq); O[vt] = __builtin_amdgcn_mfma_f32_16x16x32_bf16(sf, qs, O[vt], 0, 0, 0); }
;         }
; #pragma unroll
;         for (int nn = 0; nn < 2; ++nn) {
;             const int n = 2 * hw + nn; const f32x4 acc = nn == 0 ? acc0 : acc1;
;             const f32x4 gj = *(const f32x4*)(GI + 16 * n + 4 * fq); const int i = 16 * m + fr, j0 = 16 * n + 4 * fq; float p[4];
; #pragma unroll
;             for (int e = 0; e < 4; ++e) p[e] = (j0 + e <= i) ? acc[e] * __expf(gi_i - gj[e]) : 0.f;
;             u32x2 w; w.x = cvt_pk_bf16(p[0], p[1]); w.y = cvt_pk_bf16(p[2], p[3]); *(u32x2*)(P + (16 * m + fr) * LJ + j0) = w;
;         }
;         const float ei = __expf(gi_i);
; #pragma unroll
;         for (int vt = 0; vt < NVTW; ++vt) O[vt] = O[vt] * ei;
;     }
.LBB0_420:
	s_lshl_b32 s54, s62, 9
	s_mov_b32 s55, s12
	v_lshl_add_u64 v[218:219], v[114:115], 0, s[54:55]
	global_load_dwordx4 v[202:205], v[218:219], off
	global_load_dwordx4 v[206:209], v[218:219], off offset:64
	global_load_dwordx4 v[210:213], v[218:219], off offset:128
	global_load_dwordx4 v[214:217], v[218:219], off offset:192
	v_cvt_pk_bf16_f32 v50, v18, v19
	v_cvt_pk_bf16_f32 v51, v20, v21
	ds_write_b64 v169, v[50:51]
	v_cvt_pk_bf16_f32 v50, v22, v23
	v_cvt_pk_bf16_f32 v51, v24, v25
	ds_write_b64 v169, v[50:51] offset:4352
	v_cvt_pk_bf16_f32 v50, v26, v27
	v_cvt_pk_bf16_f32 v51, v28, v29
	ds_write_b64 v169, v[50:51] offset:8704
	v_cvt_pk_bf16_f32 v50, v30, v31
	v_cvt_pk_bf16_f32 v51, v32, v33
	ds_write_b64 v169, v[50:51] offset:13056
	v_cvt_pk_bf16_f32 v50, v34, v35
	v_cvt_pk_bf16_f32 v51, v36, v37
	ds_write_b64 v169, v[50:51] offset:17408
	v_cvt_pk_bf16_f32 v50, v38, v39
	v_cvt_pk_bf16_f32 v51, v40, v41
	ds_write_b64 v169, v[50:51] offset:21760
	v_cvt_pk_bf16_f32 v50, v42, v43
	v_cvt_pk_bf16_f32 v51, v44, v45
	ds_write_b64 v169, v[50:51] offset:26112
	v_cvt_pk_bf16_f32 v50, v46, v47
	v_cvt_pk_bf16_f32 v51, v48, v49
	ds_write_b64 v169, v[50:51] offset:30464
	s_waitcnt lgkmcnt(0)
	s_barrier
	ds_read_b32 v16, v138
	ds_read_b128 v[218:221], v139
	ds_read_b128 v[222:225], v140 offset:17408
	ds_read_b128 v[226:229], v140 offset:21760
	ds_read_b128 v[242:245], v139 offset:34816
	ds_read_b128 v[246:249], v174
	ds_read_b128 v[74:77], v174 offset:4352
	ds_read_b128 v[176:179], v174 offset:8704
	ds_read_b128 v[180:183], v174 offset:13056
	ds_read_b128 v[230:233], v139 offset:64
	ds_read_b128 v[234:237], v140 offset:17472
	ds_read_b128 v[238:241], v140 offset:21824
	s_waitcnt lgkmcnt(8)
	v_mfma_f32_16x16x32_bf16 v[54:57], v[222:225], v[218:221], 0
	v_mfma_f32_16x16x32_bf16 v[50:53], v[226:229], v[218:221], 0
	s_waitcnt lgkmcnt(3)
	v_mfma_f32_16x16x32_bf16 v[58:61], v[246:249], v[242:245], 0
	v_mfma_f32_16x16x32_bf16 v[62:65], v[74:77], v[242:245], 0
	v_mfma_f32_16x16x32_bf16 v[66:69], v[176:179], v[242:245], 0
	v_mfma_f32_16x16x32_bf16 v[70:73], v[180:183], v[242:245], 0
	ds_read_b128 v[242:245], v139 offset:34880
	ds_read_b128 v[246:249], v174 offset:64
	ds_read_b128 v[74:77], v174 offset:4416
	ds_read_b128 v[176:179], v174 offset:8768
	ds_read_b128 v[180:183], v174 offset:13120
	ds_read_b128 v[218:221], v139 offset:128
	ds_read_b128 v[222:225], v140 offset:17536
	ds_read_b128 v[226:229], v140 offset:21888
	s_waitcnt lgkmcnt(8)
	v_mfma_f32_16x16x32_bf16 v[54:57], v[234:237], v[230:233], v[54:57]
	v_mfma_f32_16x16x32_bf16 v[50:53], v[238:241], v[230:233], v[50:53]
	s_waitcnt lgkmcnt(3)
	v_mfma_f32_16x16x32_bf16 v[58:61], v[246:249], v[242:245], v[58:61]
	v_mfma_f32_16x16x32_bf16 v[62:65], v[74:77], v[242:245], v[62:65]
	v_mfma_f32_16x16x32_bf16 v[66:69], v[176:179], v[242:245], v[66:69]
	v_mfma_f32_16x16x32_bf16 v[70:73], v[180:183], v[242:245], v[70:73]
	ds_read_b128 v[242:245], v139 offset:34944
	ds_read_b128 v[246:249], v174 offset:128
	ds_read_b128 v[74:77], v174 offset:4480
	ds_read_b128 v[176:179], v174 offset:8832
	ds_read_b128 v[180:183], v174 offset:13184
	ds_read_b128 v[230:233], v139 offset:192
	ds_read_b128 v[234:237], v140 offset:17600
	ds_read_b128 v[238:241], v140 offset:21952
	s_waitcnt lgkmcnt(8)
	v_mfma_f32_16x16x32_bf16 v[54:57], v[222:225], v[218:221], v[54:57]
	v_mfma_f32_16x16x32_bf16 v[50:53], v[226:229], v[218:221], v[50:53]
	s_waitcnt lgkmcnt(3)
	v_mfma_f32_16x16x32_bf16 v[58:61], v[246:249], v[242:245], v[58:61]
	v_mfma_f32_16x16x32_bf16 v[62:65], v[74:77], v[242:245], v[62:65]
	v_mfma_f32_16x16x32_bf16 v[66:69], v[176:179], v[242:245], v[66:69]
	v_mfma_f32_16x16x32_bf16 v[70:73], v[180:183], v[242:245], v[70:73]
	ds_read_b128 v[242:245], v139 offset:35008
	ds_read_b128 v[246:249], v174 offset:192
	ds_read_b128 v[74:77], v174 offset:4544
	ds_read_b128 v[176:179], v174 offset:8896
	ds_read_b128 v[180:183], v174 offset:13248
	s_waitcnt lgkmcnt(5)
	v_mfma_f32_16x16x32_bf16 v[54:57], v[234:237], v[230:233], v[54:57]
	v_mfma_f32_16x16x32_bf16 v[50:53], v[238:241], v[230:233], v[50:53]
	s_waitcnt lgkmcnt(0)
	v_mfma_f32_16x16x32_bf16 v[58:61], v[246:249], v[242:245], v[58:61]
	v_mfma_f32_16x16x32_bf16 v[62:65], v[74:77], v[242:245], v[62:65]
	v_mfma_f32_16x16x32_bf16 v[66:69], v[176:179], v[242:245], v[66:69]
	v_mfma_f32_16x16x32_bf16 v[70:73], v[180:183], v[242:245], v[70:73]
	s_nop 7
	v_readlane_b32 s52, v255, 14
	v_readlane_b32 s53, v255, 15
	ds_read_b128 v[74:77], v141
	s_waitcnt lgkmcnt(0)
	v_sub_f32_e32 v74, v16, v74
	v_mul_f32_e32 v74, 0x3fb8aa3b, v74
	v_exp_f32_e32 v74, v74
	s_nop 0
	v_mul_f32_e32 v54, v54, v74
	v_sub_f32_e32 v74, v16, v75
	v_mul_f32_e32 v74, 0x3fb8aa3b, v74
	v_exp_f32_e32 v74, v74
	v_cndmask_b32_e64 v54, v54, 0, s[52:53]
	v_readlane_b32 s52, v255, 16
	v_readlane_b32 s53, v255, 17
	v_mul_f32_e32 v55, v55, v74
	v_sub_f32_e32 v74, v16, v76
	v_mul_f32_e32 v74, 0x3fb8aa3b, v74
	v_exp_f32_e32 v74, v74
	v_cndmask_b32_e64 v55, 0, v55, s[52:53]
	v_readlane_b32 s52, v255, 18
	v_readlane_b32 s53, v255, 19
	v_mul_f32_e32 v56, v56, v74
	v_sub_f32_e32 v74, v16, v77
	v_mul_f32_e32 v74, 0x3fb8aa3b, v74
	v_exp_f32_e32 v74, v74
	v_cndmask_b32_e64 v56, v56, 0, s[52:53]
	v_readlane_b32 s52, v255, 20
	v_readlane_b32 s53, v255, 21
	v_mul_f32_e32 v57, v57, v74
	v_cvt_pk_bf16_f32 v54, v54, v55
	s_nop 0
	v_cndmask_b32_e64 v57, v57, 0, s[52:53]
	v_cvt_pk_bf16_f32 v55, v56, v57
	ds_write_b64 v142, v[54:55]
	ds_read_b128 v[54:57], v141 offset:64
	v_readlane_b32 s52, v255, 22
	v_readlane_b32 s53, v255, 23
	s_waitcnt lgkmcnt(0)
	v_sub_f32_e32 v54, v16, v54
	v_mul_f32_e32 v54, 0x3fb8aa3b, v54
	v_exp_f32_e32 v54, v54
	s_nop 0
	v_mul_f32_e32 v50, v50, v54
	v_sub_f32_e32 v54, v16, v55
	v_mul_f32_e32 v54, 0x3fb8aa3b, v54
	v_exp_f32_e32 v54, v54
	v_cndmask_b32_e64 v50, v50, 0, s[52:53]
	v_readlane_b32 s52, v255, 24
	v_readlane_b32 s53, v255, 25
	v_mul_f32_e32 v51, v51, v54
	v_sub_f32_e32 v54, v16, v56
	v_mul_f32_e32 v54, 0x3fb8aa3b, v54
	v_exp_f32_e32 v54, v54
	v_cndmask_b32_e64 v51, 0, v51, s[52:53]
	v_readlane_b32 s52, v255, 26
	v_readlane_b32 s53, v255, 27
	v_mul_f32_e32 v52, v52, v54
	v_sub_f32_e32 v54, v16, v57
	v_mul_f32_e32 v54, 0x3fb8aa3b, v54
	v_exp_f32_e32 v54, v54
	v_mul_f32_e32 v16, 0x3fb8aa3b, v16
	v_exp_f32_e32 v16, v16
	v_cndmask_b32_e64 v52, v52, 0, s[52:53]
	v_readlane_b32 s52, v255, 28
	v_mul_f32_e32 v53, v53, v54
	v_readlane_b32 s53, v255, 29
	v_cvt_pk_bf16_f32 v50, v50, v51
	v_pk_mul_f32 v[54:55], v[16:17], v[62:63] op_sel_hi:[0,1]
	v_pk_mul_f32 v[56:57], v[16:17], v[64:65] op_sel_hi:[0,1]
	v_cndmask_b32_e64 v53, v53, 0, s[52:53]
	v_cvt_pk_bf16_f32 v51, v52, v53
	ds_write_b64 v142, v[50:51] offset:32
	v_pk_mul_f32 v[50:51], v[16:17], v[58:59] op_sel_hi:[0,1]
	v_pk_mul_f32 v[52:53], v[16:17], v[60:61] op_sel_hi:[0,1]
	v_pk_mul_f32 v[58:59], v[16:17], v[66:67] op_sel_hi:[0,1]
	v_pk_mul_f32 v[60:61], v[16:17], v[68:69] op_sel_hi:[0,1]
	v_pk_mul_f32 v[62:63], v[16:17], v[70:71] op_sel_hi:[0,1]
	v_pk_mul_f32 v[64:65], v[16:17], v[72:73] op_sel_hi:[0,1]
	s_waitcnt lgkmcnt(0)
	s_barrier
; template <int DK, int DV, bool SEPQ> ...
;     ...
;     __syncthreads();
; #pragma unroll
;     for (int ks = 0; ks < 2; ++ks) { const bf16x8 pf = *(const bf16x8*)(P + (16 * m + fr) * LJ + 32 * ks + 8 * fq);
; #pragma unroll
;         for (int vt = 0; vt < NVTW; ++vt) { const bf16x8 vf = *(const bf16x8*)(VT + (16 * (hw * NVTW + vt) + fr) * LJ + 32 * ks + 8 * fq); O[vt] = __builtin_amdgcn_mfma_f32_16x16x32_bf16(vf, pf, O[vt], 0, 0, 0); } }
; #pragma unroll
;     for (int ct = 0; ct < NCTW; ++ct) { const int ctg = wid * NCTW + ct; const f32x4 dec = *(const f32x4*)(SDEC + 16 * ctg + 4 * fq);
; #pragma unroll
;         for (int vt = 0; vt < NVT; ++vt) S[ct][vt] = S[ct][vt] * dec;
; #pragma unroll
;         for (int ks = 0; ks < 2; ++ks) { const bf16x8 kf = *(const bf16x8*)(KT + (16 * ctg + fr) * LJ + 32 * ks + 8 * fq);
; #pragma unroll
;             for (int vt = 0; vt < NVT; ++vt) { const bf16x8 vf = *(const bf16x8*)(VT2 + (16 * vt + fr) * LJ + 32 * ks + 8 * fq); S[ct][vt] = __builtin_amdgcn_mfma_f32_16x16x32_bf16(kf, vf, S[ct][vt], 0, 0, 0); } } }
; __device__ __forceinline__ void hg_block(ArgsP a_, int jl, unsigned char* smem) { const ArgsP a = a_;
;     ...
;         { float ss = 0.f;
; #pragma unroll
;           for (int vt = 0; vt < 4; ++vt) ss += (O[vt][0] * O[vt][0] + O[vt][1] * O[vt][1]) + (O[vt][2] * O[vt][2] + O[vt][3] * O[vt][3]);
;           ss += __shfl_xor(ss, 16); ss += __shfl_xor(ss, 32); if (fq == 0) RSm[irow * 2 + hw] = ss; }
	ds_read_b128 v[66:69], v143
	ds_read_b128 v[70:73], v170
	s_waitcnt lgkmcnt(0)
	v_mfma_f32_16x16x32_bf16 v[50:53], v[70:73], v[66:69], v[50:53]
	ds_read_b128 v[70:73], v170 offset:2304
	s_waitcnt lgkmcnt(0)
	v_mfma_f32_16x16x32_bf16 v[54:57], v[70:73], v[66:69], v[54:57]
	ds_read_b128 v[70:73], v170 offset:4608
	s_waitcnt lgkmcnt(0)
	v_mfma_f32_16x16x32_bf16 v[70:73], v[70:73], v[66:69], v[58:61]
	s_nop 2
	ds_read_b128 v[58:61], v170 offset:6912
	s_waitcnt lgkmcnt(0)
	v_mfma_f32_16x16x32_bf16 v[66:69], v[58:61], v[66:69], v[62:65]
	ds_read_b128 v[74:77], v143 offset:64
	ds_read_b128 v[58:61], v170 offset:64
	s_waitcnt lgkmcnt(0)
	v_mfma_f32_16x16x32_bf16 v[62:65], v[58:61], v[74:77], v[50:53]
	s_nop 2
	ds_read_b128 v[50:53], v170 offset:2368
	s_waitcnt lgkmcnt(0)
	v_mfma_f32_16x16x32_bf16 v[58:61], v[50:53], v[74:77], v[54:57]
	ds_read_b128 v[50:53], v170 offset:4672
	s_nop 0
	v_mul_f32_e32 v16, v63, v63
	v_fmac_f32_e32 v16, v62, v62
	s_waitcnt lgkmcnt(0)
	v_mfma_f32_16x16x32_bf16 v[54:57], v[50:53], v[74:77], v[70:73]
	ds_read_b128 v[50:53], v170 offset:6976
	s_waitcnt lgkmcnt(0)
	v_mfma_f32_16x16x32_bf16 v[50:53], v[50:53], v[74:77], v[66:69]
	s_nop 2
	ds_read_b128 v[66:69], v171
	s_waitcnt lgkmcnt(0)
	v_pk_mul_f32 v[20:21], v[20:21], v[68:69]
	v_pk_mul_f32 v[18:19], v[18:19], v[66:67]
	v_pk_mul_f32 v[22:23], v[22:23], v[66:67]
	v_pk_mul_f32 v[24:25], v[24:25], v[68:69]
	v_pk_mul_f32 v[26:27], v[26:27], v[66:67]
	v_pk_mul_f32 v[28:29], v[28:29], v[68:69]
	v_pk_mul_f32 v[30:31], v[30:31], v[66:67]
	v_pk_mul_f32 v[32:33], v[32:33], v[68:69]
	v_pk_mul_f32 v[34:35], v[34:35], v[66:67]
	v_pk_mul_f32 v[36:37], v[36:37], v[68:69]
	v_pk_mul_f32 v[38:39], v[38:39], v[66:67]
	v_pk_mul_f32 v[40:41], v[40:41], v[68:69]
	v_pk_mul_f32 v[42:43], v[42:43], v[66:67]
	v_pk_mul_f32 v[44:45], v[44:45], v[68:69]
	v_pk_mul_f32 v[46:47], v[46:47], v[66:67]
	v_pk_mul_f32 v[48:49], v[48:49], v[68:69]
	ds_read_b128 v[66:69], v144 offset:52224
	ds_read_b128 v[70:73], v172
	s_waitcnt lgkmcnt(0)
	v_mfma_f32_16x16x32_bf16 v[18:21], v[66:69], v[70:73], v[18:21]
	ds_read_b128 v[70:73], v172 offset:2304
	s_waitcnt lgkmcnt(0)
	v_mfma_f32_16x16x32_bf16 v[22:25], v[66:69], v[70:73], v[22:25]
	ds_read_b128 v[70:73], v172 offset:4608
	s_waitcnt lgkmcnt(0)
	v_mfma_f32_16x16x32_bf16 v[26:29], v[66:69], v[70:73], v[26:29]
	ds_read_b128 v[70:73], v172 offset:6912
	s_waitcnt lgkmcnt(0)
	v_mfma_f32_16x16x32_bf16 v[30:33], v[66:69], v[70:73], v[30:33]
	ds_read_b128 v[70:73], v172 offset:9216
	s_waitcnt lgkmcnt(0)
	v_mfma_f32_16x16x32_bf16 v[34:37], v[66:69], v[70:73], v[34:37]
	ds_read_b128 v[70:73], v172 offset:11520
	s_waitcnt lgkmcnt(0)
	v_mfma_f32_16x16x32_bf16 v[38:41], v[66:69], v[70:73], v[38:41]
	ds_read_b128 v[70:73], v172 offset:13824
	s_waitcnt lgkmcnt(0)
	v_mfma_f32_16x16x32_bf16 v[42:45], v[66:69], v[70:73], v[42:45]
	ds_read_b128 v[70:73], v172 offset:16128
	s_waitcnt lgkmcnt(0)
	v_mfma_f32_16x16x32_bf16 v[46:49], v[66:69], v[70:73], v[46:49]
	ds_read_b128 v[66:69], v144 offset:52288
	ds_read_b128 v[70:73], v172 offset:64
	s_waitcnt lgkmcnt(0)
	v_mfma_f32_16x16x32_bf16 v[18:21], v[66:69], v[70:73], v[18:21]
	ds_read_b128 v[70:73], v172 offset:2368
	s_waitcnt lgkmcnt(0)
	v_mfma_f32_16x16x32_bf16 v[22:25], v[66:69], v[70:73], v[22:25]
	ds_read_b128 v[70:73], v172 offset:4672
	s_waitcnt lgkmcnt(0)
	v_mfma_f32_16x16x32_bf16 v[26:29], v[66:69], v[70:73], v[26:29]
	ds_read_b128 v[70:73], v172 offset:6976
	s_waitcnt lgkmcnt(0)
	v_mfma_f32_16x16x32_bf16 v[30:33], v[66:69], v[70:73], v[30:33]
	ds_read_b128 v[70:73], v172 offset:9280
	s_waitcnt lgkmcnt(0)
	v_mfma_f32_16x16x32_bf16 v[34:37], v[66:69], v[70:73], v[34:37]
	ds_read_b128 v[70:73], v172 offset:11584
	s_waitcnt lgkmcnt(0)
	v_mfma_f32_16x16x32_bf16 v[38:41], v[66:69], v[70:73], v[38:41]
	ds_read_b128 v[70:73], v172 offset:13888
	s_waitcnt lgkmcnt(0)
	v_mfma_f32_16x16x32_bf16 v[42:45], v[66:69], v[70:73], v[42:45]
	ds_read_b128 v[70:73], v172 offset:16192
	s_waitcnt lgkmcnt(0)
	v_mfma_f32_16x16x32_bf16 v[46:49], v[66:69], v[70:73], v[46:49]
	v_mul_f32_e32 v66, v65, v65
	v_fmac_f32_e32 v66, v64, v64
	v_add_f32_e32 v16, v16, v66
	v_mul_f32_e32 v66, v59, v59
	v_mul_f32_e32 v67, v61, v61
	v_fmac_f32_e32 v66, v58, v58
	v_fmac_f32_e32 v67, v60, v60
	v_add_f32_e32 v66, v66, v67
	v_add_f32_e32 v16, v16, v66
	v_mul_f32_e32 v66, v55, v55
	v_mul_f32_e32 v67, v57, v57
	v_fmac_f32_e32 v66, v54, v54
	v_fmac_f32_e32 v67, v56, v56
	v_add_f32_e32 v66, v66, v67
	v_add_f32_e32 v16, v16, v66
	v_mul_f32_e32 v66, v51, v51
	v_mul_f32_e32 v67, v53, v53
	v_fmac_f32_e32 v66, v50, v50
	v_fmac_f32_e32 v67, v52, v52
	v_add_f32_e32 v66, v66, v67
	v_and_b32_e32 v67, 64, v188
	v_add_f32_e32 v16, v16, v66
	v_xor_b32_e32 v66, 16, v188
	v_add_u32_e32 v67, 64, v67
	v_cmp_lt_i32_e32 vcc, v66, v67
	s_nop 1
	v_cndmask_b32_e32 v66, v188, v66, vcc
	v_lshlrev_b32_e32 v66, 2, v66
	ds_bpermute_b32 v66, v66, v16
	s_waitcnt lgkmcnt(0)
	v_add_f32_e32 v16, v16, v66
	v_xor_b32_e32 v66, 32, v188
	v_cmp_lt_i32_e32 vcc, v66, v67
	s_nop 1
	v_cndmask_b32_e32 v66, v188, v66, vcc
	v_lshlrev_b32_e32 v66, 2, v66
	ds_bpermute_b32 v66, v66, v16
	s_mov_b64 s[52:53], exec
	v_readlane_b32 s54, v255, 30
	v_readlane_b32 s55, v255, 31
	s_and_b64 s[54:55], s[52:53], s[54:55]
	s_mov_b64 exec, s[54:55]
	s_cbranch_execz .LBB0_438
	s_waitcnt lgkmcnt(0)
	v_add_f32_e32 v16, v16, v66
	ds_write_b32 v173, v16
